# XCD barrier: leader L2 write-back skipped after phases 3/7/13/19 whose stores are all write-through
# baseline (speedup 1.0000x reference)
.LBB0_1058:
	s_andn2_saveexec_b64 s[10:11], s[10:11]
	s_cbranch_execz .LBB0_1078
	s_mov_b64 s[10:11], exec
	s_mov_b32 s101, 0x82088
	s_bitcmp1_b32 s101, s86
	s_cbranch_scc1 .Lxb_nowb
	buffer_wbl2 sc1
.Lxb_nowb:
	s_waitcnt lgkmcnt(0)
	s_waitcnt vmcnt(0)
	v_mbcnt_lo_u32_b32 v1, s10, 0
	v_mbcnt_hi_u32_b32 v1, s11, v1
	v_cmp_eq_u32_e32 vcc, 0, v1
	s_and_saveexec_b64 s[12:13], vcc
	s_cbranch_execz .LBB0_1061
	s_bcnt1_i32_b64 s0, s[10:11]
	v_mov_b32_e32 v2, s0
	v_mov_b32_e32 v3, 0x494e000
	global_atomic_add v2, v3, v2, s[90:91] offset:1024 sc0
